# grid barrier: global-counter poll loop without the s_sleep between polls
# speedup vs baseline: 1.0036x; 1.0023x over previous
.LBB0_1397:
	s_and_b32 s12, s3, 0xff
	s_mov_b64 s[10:11], -1
	s_cmp_lg_u32 s12, 0
	s_mov_b64 s[14:15], -1
	s_cbranch_scc0 .LBB0_1400
	s_and_b64 vcc, exec, s[14:15]
	s_cbranch_vccz .LBB0_1396
